# retention phase: one static s_setprio 1 for waves 4-7 (reset at phase exit)
# baseline (speedup 1.0000x reference)
; #define LAS __attribute__((address_space(3)))
; __device__ __forceinline__ float rms_r(float ss) { return __builtin_amdgcn_rsqf(ss * (1.0f / DM) + RMS_EPS); }
; #define LDS_BAR() do { asm volatile("s_waitcnt lgkmcnt(0)" ::: "memory"); __builtin_amdgcn_s_barrier(); asm volatile("" ::: "memory"); } while (0)
; __device__ __forceinline__ void ret_unit(LAS unsigned char* lds, bf16_t* QKV, float* gn, int b, int h, int vs, bool commit, const float* s00p, const float* ss3, bool skel = false) {
;     const int tid = threadIdx.x, lane = tid & 63, w = tid >> 6, fr = lane & 15, fq = lane >> 4;
;     LAS bf16_t* Kb = (LAS bf16_t*)lds;
;     LAS bf16_t* Ql = Kb + 2 * 64 * 264;
;     LAS bf16_t* Vb = Ql + 64 * 264;
;     LAS bf16_t* Pl = Vb + 2 * 64 * 136;
;     LAS float* st = (LAS float*)(Pl + 64 * 72);
;     const float l2g = __builtin_amdgcn_logf(1.0f - __builtin_amdgcn_exp2f(-5.0f - (float)h));
;     const float cd = __builtin_amdgcn_exp2f(64.f * l2g);
;     f32x4 state[16];
; #pragma unroll
;     for (int m = 0; m < 16; ++m) state[m] = (f32x4){0.f, 0.f, 0.f, 0.f};
;     const float s00 = s00p[b * 4 + h] * rms_r(ss3[(size_t)b * SEQ]) * rms_r(ss3[(size_t)b * SEQ]) * 0.0625f;
;     const int si = w & 3, ti0 = 2 * (w >> 2);
;     u32x4 pq[4], pkv[4], pv[2];
;     const int ls = tid & 63, lc8 = tid >> 6;
;     ...
;     RET_LOAD(0);
;     LDS_BAR();
;     RET_STAGE(Kb, Vb);
;     RET_LOAD(1);
;     if (tid < 128) st[tid] = 0.f;
;     LDS_BAR();
;     for (int c = 0; c < 32; ++c) {
;         const size_t trow0 = (size_t)b * SEQ + 64 * c;
;         LAS bf16_t* Kl = Kb + (c & 1) * (64 * 264); LAS bf16_t* Vl = Vb + (c & 1) * (64 * 136);
;         LAS bf16_t* Kn = Kb + ((c & 1) ^ 1) * (64 * 264); LAS bf16_t* Vn = Vb + ((c & 1) ^ 1) * (64 * 136);
;     ...
;         f32x4 oacc[4];
; #pragma unroll
;         for (int n = 0; n < 4; ++n) oacc[n] = (f32x4){0.f, 0.f, 0.f, 0.f};
;         if (!skel) {
;         { f32x4 sv[2] = {(f32x4){0.f, 0.f, 0.f, 0.f}, (f32x4){0.f, 0.f, 0.f, 0.f}};
;           bf16x8 ka[3], qb[3][2];
; __global__ void __launch_bounds__(NTHR, 2) fwd_megakernel(Args a) {
;     ...
;     if (IN(PH_L1 + 1)) {
;         for (int u = bx; u < 256; u += G) { const int xcd = u & 7, t = u >> 3, vs = t & 3, pair = xcd + 8 * (t >> 2);
;             ret_unit(lds, BIG, GN, pair >> 2, pair & 3, vs, true, S00, SS + 3 * MT); } }
.LBB0_1130:
	v_readlane_b32 s52, v254, 6
	s_cmp_lt_i32 s52, 10
	s_cselect_b64 s[6:7], -1, 0
	s_add_u32 s0, s50, 0x180000
	s_addc_u32 s1, s51, 0
	s_and_b64 s[34:35], s[6:7], s[4:5]
	s_xor_b64 s[4:5], s[34:35], -1
	s_cmpk_gt_i32 s2, 0xff
	s_cselect_b64 s[6:7], -1, 0
	s_or_b64 s[4:5], s[4:5], s[6:7]
	v_readlane_b32 s53, v254, 7
	v_readlane_b32 s54, v254, 8
	v_readlane_b32 s55, v254, 9
	s_and_b64 vcc, exec, s[4:5]
	s_cbranch_vccnz .LBB0_1160
	v_and_b32_e32 v128, 63, v176
	s_add_u32 s33, s50, 0x60000
	v_mul_u32_u24_e32 v2, 0x108, v128
	s_addc_u32 s70, s51, 0
	v_bfe_u32 v3, v176, 6, 2
	s_add_i32 s38, 0, 0x10800
	v_lshlrev_b32_e32 v4, 1, v2
	v_lshlrev_b32_e32 v2, 4, v224
	v_and_b32_e32 v130, 15, v176
	v_add3_u32 v129, s38, v4, v2
	v_add3_u32 v131, 0, v4, v2
	v_mul_u32_u24_e32 v4, 0x110, v128
	s_add_i32 s8, 0, 0x18c00
	v_lshlrev_b32_e32 v6, 4, v3
	s_waitcnt lgkmcnt(0)
	v_bfe_u32 v1, v176, 4, 2
	v_add3_u32 v135, s8, v4, v2
	v_or_b32_e32 v4, v6, v130
	s_waitcnt vmcnt(0)
	v_lshlrev_b32_e32 v10, 5, v224
	v_and_b32_e32 v12, 1, v176
	v_mul_u32_u24_e32 v163, 0x210, v4
	v_lshlrev_b32_e32 v4, 2, v1
	v_add_u32_e32 v11, s8, v10
	v_lshlrev_b32_e32 v132, 2, v12
	v_lshrrev_b32_e32 v12, 3, v176
	s_movk_i32 s8, 0x60
	v_lshlrev_b32_e32 v5, 2, v176
	s_add_i32 s71, 0, 0x23800
	v_lshlrev_b32_e32 v164, 3, v1
	v_and_b32_e32 v7, 48, v176
	v_or_b32_e32 v1, v6, v4
	v_and_or_b32 v12, v12, s8, v130
	v_add_u32_e32 v162, s71, v5
	s_movk_i32 s42, 0x210
	v_add_u32_e32 v8, s38, v7
	s_add_i32 s9, 0, 0x21400
	v_lshlrev_b32_e32 v6, 5, v3
	v_and_b32_e32 v5, 12, v5
	v_or_b32_e32 v14, 16, v12
	v_or_b32_e32 v15, 2, v1
	v_or_b32_e32 v16, 3, v1
	v_add3_u32 v6, s9, v6, v164
	v_lshlrev_b32_e32 v165, 1, v5
	v_add_u32_e32 v5, s9, v7
	v_mul_u32_u24_e32 v13, 0x210, v12
	v_mad_u32_u24 v167, v12, s42, v8
	v_cmp_lt_u32_e64 s[8:9], v12, v1
	v_cmp_gt_u32_e64 s[10:11], v12, v1
	v_cmp_lt_u32_e64 s[12:13], v12, v15
	v_cmp_lt_u32_e64 s[14:15], v12, v16
	v_or_b32_e32 v169, v12, v3
	v_mul_u32_u24_e32 v3, 0x90, v12
	v_cmp_lt_u32_e64 s[16:17], v14, v1
	v_cmp_gt_u32_e64 s[18:19], v14, v1
	v_cmp_lt_u32_e64 s[20:21], v14, v15
	v_cmp_lt_u32_e64 s[22:23], v14, v16
	v_mov_b32_e32 v12, 0x2100
	v_mov_b32_e32 v14, 0x4200
	v_mov_b32_e32 v15, 0x6300
	v_mul_u32_u24_e32 v1, 0x210, v130
	v_mad_u32_u24 v12, v130, s42, v12
	v_mad_u32_u24 v14, v130, s42, v14
	v_mad_u32_u24 v15, v130, s42, v15
	v_add3_u32 v170, s38, v1, v164
	v_add3_u32 v171, s38, v12, v164
	v_add3_u32 v172, s38, v14, v164
	v_add3_u32 v173, s38, v15, v164
	s_add_i32 s38, 0, 0x10880
	v_add3_u32 v174, s38, v1, v164
	v_add3_u32 v175, s38, v12, v164
	v_add3_u32 v177, s38, v14, v164
	v_add3_u32 v178, s38, v15, v164
	s_add_i32 s38, 0, 0x108c0
	v_add3_u32 v179, s38, v1, v164
	v_add3_u32 v180, s38, v12, v164
	v_add3_u32 v181, s38, v14, v164
	v_add3_u32 v182, s38, v15, v164
	s_add_i32 s38, 0, 0x10900
	v_add3_u32 v183, s38, v1, v164
	v_add3_u32 v184, s38, v12, v164
	v_add3_u32 v185, s38, v14, v164
	v_add3_u32 v186, s38, v15, v164
	s_add_i32 s38, 0, 0x10940
	v_bfe_u32 v9, v176, 2, 2
	v_add3_u32 v187, s38, v1, v164
	v_add3_u32 v188, s38, v12, v164
	v_add3_u32 v189, s38, v14, v164
	v_add3_u32 v190, s38, v15, v164
	s_add_i32 s38, 0, 0x10980
	v_lshlrev_b32_e32 v0, 3, v224
	v_or_b32_e32 v9, v164, v9
	v_lshrrev_b32_e32 v134, 1, v176
	v_add3_u32 v191, s38, v1, v164
	v_add3_u32 v192, s38, v12, v164
	v_add3_u32 v193, s38, v14, v164
	v_add3_u32 v194, s38, v15, v164
	s_add_i32 s38, 0, 0x109c0
	v_add3_u32 v201, 0, v163, v7
	v_lshlrev_b32_e32 v7, 13, v130
	v_mov_b32_e32 v133, 0
	s_movk_i32 s4, 0x80
	v_add3_u32 v195, s38, v1, v164
	v_add3_u32 v196, s38, v12, v164
	v_add3_u32 v197, s38, v14, v164
	v_add3_u32 v198, s38, v15, v164
	v_mul_u32_u24_e32 v1, 0x90, v130
	v_mul_u32_u24_e32 v12, 0x110, v9
	v_lshl_or_b32 v138, v128, 13, v2
	v_or3_b32 v142, v7, v10, v164
	v_lshlrev_b32_e32 v7, 5, v134
	s_mov_b32 s38, 0x180000
	v_lshlrev_b32_e32 v146, 1, v0
	v_mbcnt_lo_u32_b32 v0, -1, 0
	s_mov_b32 s39, 0
	v_cmp_gt_u32_e64 s[4:5], s4, v176
	v_cmp_gt_u32_e64 s[6:7], 16, v128
	v_lshlrev_b32_e32 v166, 3, v130
	v_lshl_add_u64 v[136:137], s[0:1], 0, v[132:133]
	v_add_u32_e32 v168, 0x2100, v167
	v_mul_u32_u24_e32 v199, 0x210, v9
	v_add3_u32 v200, v11, v165, v12
	v_mov_b32_e32 v139, v133
	v_or_b32_e32 v140, 0xe300800, v138
	v_mov_b32_e32 v141, v133
	v_mov_b32_e32 v143, v133
	s_lshl_b32 s73, s2, 4
	s_lshl_b32 s74, s54, 4
	v_or3_b32 v144, v7, v132, s38
	v_mov_b32_e32 v145, v133
	s_mov_b64 s[42:43], 0x41000
	s_movk_i32 s75, 0x1000
	s_mov_b64 s[52:53], 0x80000
	s_mov_b32 s76, 0x80000
	s_mov_b64 s[54:55], 0x81000
	v_mbcnt_hi_u32_b32 v202, -1, v0
	s_mov_b64 s[56:57], 0x800
	v_lshlrev_b32_e32 v132, 1, v2
	v_lshlrev_b32_e32 v148, 1, v4
	v_add_u32_e32 v203, v8, v13
	v_add_u32_e32 v204, v6, v3
	v_add_u32_e32 v205, v5, v1
	s_mov_b32 s77, s2
	s_mov_b32 s78, s2
	v_lshrrev_b32_e32 v129, 5, v176
	v_mul_u32_u24_e32 v129, 0x210, v129
	v_and_b32_e32 v255, 31, v176
	v_lshl_add_u32 v129, v255, 4, v129
	v_mov_b32_e32 v131, v129
	v_add_u32_e32 v129, 0x10800, v129
	v_lshrrev_b32_e32 v135, 4, v176
	v_mul_u32_u24_e32 v135, 0x110, v135
	v_lshl_add_u32 v135, v130, 4, v135
	v_add_u32_e32 v135, 0x18c00, v135
	v_lshrrev_b32_e32 v146, 5, v176
	v_lshlrev_b32_e32 v255, 4, v255
	v_lshl_or_b32 v146, v146, 13, v255
	v_or_b32_e32 v140, 0xe300800, v146
	v_lshrrev_b32_e32 v138, 4, v176
	v_lshlrev_b32_e32 v255, 4, v130
	v_lshl_or_b32 v138, v138, 13, v255
	s_mov_b64 s[84:85], 0x20000
	s_mov_b64 s[86:87], 0x40000
	v_and_b32_e32 v255, 16, v176
	v_lshlrev_b32_e32 v255, 4, v255
	v_and_b32_e32 v0, 32, v176
	v_lshl_or_b32 v255, v0, 2, v255
	v_lshl_or_b32 v255, v130, 3, v255
	v_add_u32_e32 v255, 0x23800, v255
	v_lshrrev_b32_e32 v129, 5, v176
	v_mul_u32_u24_e32 v129, 0x210, v129
	v_and_b32_e32 v0, 28, v176
	v_lshl_add_u32 v129, v0, 4, v129
	v_and_b32_e32 v0, 1, v176
	v_lshl_add_u32 v129, v0, 5, v129
	v_and_b32_e32 v0, 2, v176
	v_lshl_add_u32 v129, v0, 2, v129
	v_add_u32_e32 v129, 0x10800, v129
	v_mul_u32_u24_e32 v170, 0x210, v130
	v_lshl_add_u32 v170, v164, 1, v170
	v_add_u32_e32 v170, 0x10800, v170
	v_add_u32_e32 v201, 0x8400, v163
	v_add_u32_e32 v201, v201, v164
	v_readfirstlane_b32 s86, v224
	s_nop 3
	s_cmp_ge_u32 s86, 4
	s_cbranch_scc0 .Lp9_prio_done
	s_setprio 1
.Lp9_prio_done:
	s_mov_b64 s[86:87], 0x40000
	s_branch .LBB0_1133

; __global__ void __launch_bounds__(NTHR, 2) fwd_megakernel(Args a) {
;     ...
;     if (IN(PH_L1 + 1)) {
;         for (int u = bx; u < 256; u += G) { const int xcd = u & 7, t = u >> 3, vs = t & 3, pair = xcd + 8 * (t >> 2);
;             ret_unit(lds, BIG, GN, pair >> 2, pair & 3, vs, true, S00, SS + 3 * MT); } }
.LBB0_1159:
	s_setprio 0
	v_readlane_b32 s52, v254, 6
	v_readlane_b32 s53, v254, 7
	v_readlane_b32 s54, v254, 8
	v_readlane_b32 s55, v254, 9
